# v6 + attention fast loops: LDS-DMA via SGPR base + 32-bit VGPR offset (no 64-bit address VALU), dropped inline-asm hazard s_nop padding (hazards re-checked)
# speedup vs baseline: 1.0035x; 1.0035x over previous
.LBB0_914:
	s_cmpk_lt_u32 s47, 0x41
	s_cselect_b64 s[2:3], -1, 0
	s_cmp_gt_u32 s47, 64
	s_cselect_b64 s[42:43], -1, 0
	s_and_b64 vcc, exec, s[42:43]
	s_cbranch_vccnz .LBB0_916
	s_cmp_lt_u32 s47, 61
	s_cselect_b32 s44, s40, s21
	s_add_i32 s44, s44, s41
	s_sub_i32 s44, s44, 64
	s_mul_hi_i32 s45, s44, 0x600
	s_mulk_i32 s44, 0x600
	s_add_u32 s44, s14, s44
	s_addc_u32 s45, s15, s45
	s_lshl_b32 s49, s48, 14
	s_add_i32 s49, s58, s49
	s_mov_b32 m0, s49
	s_nop 0
	global_load_lds_dwordx4 v198, s[44:45]
	s_add_i32 m0, s49, 0x400
	s_nop 0
	global_load_lds_dwordx4 v194, s[44:45]
.LBB0_916:
	s_cmp_lt_u32 s47, 62
	s_cselect_b32 s44, s40, s21
	s_add_i32 s44, s44, s41
	s_addk_i32 s44, 0xff80
	s_ashr_i32 s45, s44, 31
	s_lshl_b64 s[44:45], s[44:45], 1
	s_add_u32 s44, s39, s44
	s_addc_u32 s45, s67, s45
	s_add_i32 s49, s46, 0xffffc000
	s_and_b32 s49, s49, 0xc000
	s_add_i32 s49, s58, s49
	s_add_i32 m0, s49, 0xc000
	v_mov_b32_e32 v176, v206
	global_load_lds_dwordx4 v196, s[44:45]
	v_lshl_add_u64 v[140:141], s[44:45], 0, v[192:193]
	s_add_i32 m0, s49, 0xc400
	s_add_i32 s44, s48, 1
	global_load_lds_dwordx4 v[140:141], off
	s_cmp_lg_u32 s48, 2
	s_cselect_b32 s48, s44, 0
	s_lshl_b32 s44, s48, 14
	s_and_b32 s49, s46, 0xc000
	s_add_i32 s68, s44, 0
	v_mov_b32_e32 v181, v205
	s_add_i32 s44, s49, 0
	v_add_u32_e32 v156, s44, v176
	ds_read_b128 v[140:143], v156 offset:49152
	ds_read_b128 v[148:151], v156 offset:53248
	ds_read_b128 v[152:155], v156 offset:57344
	ds_read_b128 v[156:159], v156 offset:61440
	s_waitcnt lgkmcnt(0)
	v_mfma_f32_32x32x16_bf16 v[80:95], v[140:143], v[144:147], v[80:95]
	v_xad_u32 v177, v176, 32, s44
	ds_read_b128 v[140:143], v177 offset:49152
	v_mfma_f32_32x32x16_bf16 v[64:79], v[148:151], v[144:147], v[64:79]
	ds_read_b128 v[148:151], v177 offset:53248
	v_mfma_f32_32x32x16_bf16 v[16:31], v[152:155], v[144:147], v[16:31]
	ds_read_b128 v[152:155], v177 offset:57344
	v_mfma_f32_32x32x16_bf16 v[0:15], v[156:159], v[144:147], v[0:15]
	ds_read_b128 v[144:147], v177 offset:61440
	s_waitcnt lgkmcnt(0)
	v_mfma_f32_32x32x16_bf16 v[80:95], v[140:143], v[128:131], v[80:95]
	v_xad_u32 v156, v176, 64, s44
	ds_read_b128 v[140:143], v156 offset:49152
	v_mfma_f32_32x32x16_bf16 v[64:79], v[148:151], v[128:131], v[64:79]
	ds_read_b128 v[148:151], v156 offset:53248
	v_mfma_f32_32x32x16_bf16 v[16:31], v[152:155], v[128:131], v[16:31]
	ds_read_b128 v[152:155], v156 offset:57344
	v_mfma_f32_32x32x16_bf16 v[0:15], v[144:147], v[128:131], v[0:15]
	ds_read_b128 v[128:131], v156 offset:61440
	s_waitcnt lgkmcnt(0)
	v_mfma_f32_32x32x16_bf16 v[80:95], v[140:143], v[132:135], v[80:95]
	v_xor_b32_e32 v140, 0x60, v176
	v_add_u32_e32 v156, s44, v140
	ds_read_b128 v[140:143], v156 offset:49152
	v_mfma_f32_32x32x16_bf16 v[64:79], v[148:151], v[132:135], v[64:79]
	ds_read_b128 v[144:147], v156 offset:53248
	v_mfma_f32_32x32x16_bf16 v[16:31], v[152:155], v[132:135], v[16:31]
	ds_read_b128 v[148:151], v156 offset:57344
	v_mfma_f32_32x32x16_bf16 v[0:15], v[128:131], v[132:135], v[0:15]
	ds_read_b128 v[128:131], v156 offset:61440
	s_waitcnt lgkmcnt(0)
	v_mfma_f32_32x32x16_bf16 v[80:95], v[140:143], v[136:139], v[80:95]
	v_add_u32_e32 v140, s68, v181
	ds_read_b128 v[132:135], v140
	v_mfma_f32_32x32x16_bf16 v[64:79], v[144:147], v[136:139], v[64:79]
	ds_read_b128 v[140:143], v140 offset:8192
	v_mfma_f32_32x32x16_bf16 v[16:31], v[148:151], v[136:139], v[16:31]
	v_xad_u32 v144, v181, 32, s68
	ds_read_b128 v[176:179], v144
	v_mfma_f32_32x32x16_bf16 v[0:15], v[128:131], v[136:139], v[0:15]
	ds_read_b128 v[182:185], v144 offset:8192
	s_waitcnt lgkmcnt(0)
	v_mfma_f32_32x32x16_bf16 v[144:159], v[132:135], v[160:163], 0
	v_xad_u32 v216, v181, 64, s68
	ds_read_b128 v[186:189], v216
	v_exp_f32_e32 v220, v112
	v_exp_f32_e32 v221, v113
	v_exp_f32_e32 v222, v114
	v_exp_f32_e32 v223, v115
	v_mfma_f32_32x32x16_bf16 v[128:143], v[140:143], v[160:163], 0
	ds_read_b128 v[216:219], v216 offset:8192
	v_exp_f32_e32 v224, v116
	v_exp_f32_e32 v225, v117
	v_exp_f32_e32 v226, v118
	v_exp_f32_e32 v227, v119
	v_mfma_f32_32x32x16_bf16 v[144:159], v[176:179], v[164:167], v[144:159]
	v_xor_b32_e32 v112, 0x60, v181
	v_add_u32_e32 v181, s68, v112
	ds_read_b128 v[116:119], v181
	v_exp_f32_e32 v228, v120
	v_exp_f32_e32 v229, v121
	v_exp_f32_e32 v230, v122
	v_exp_f32_e32 v231, v123
	v_pk_add_f32 v[122:123], v[222:223], 0 op_sel_hi:[1,0]
	v_pk_add_f32 v[120:121], v[220:221], 0 op_sel_hi:[1,0]
	v_cvt_pk_bf16_f32 v112, v220, v221
	v_cvt_pk_bf16_f32 v113, v222, v223
	v_cvt_pk_bf16_f32 v114, v224, v225
	v_cvt_pk_bf16_f32 v115, v226, v227
	v_pk_add_f32 v[122:123], v[226:227], v[122:123]
	v_pk_add_f32 v[120:121], v[224:225], v[120:121]
	v_mfma_f32_32x32x16_bf16 v[128:143], v[182:185], v[164:167], v[128:143]
	ds_read_b128 v[176:179], v181 offset:8192
	v_exp_f32_e32 v124, v124
	v_exp_f32_e32 v125, v125
	v_exp_f32_e32 v126, v126
	v_exp_f32_e32 v127, v127
	s_waitcnt lgkmcnt(0)
	v_mfma_f32_32x32x16_bf16 v[144:159], v[186:189], v[168:171], v[144:159]
	v_add_f32_e64 v122, v230, v122
	v_add_f32_e64 v123, v231, v123
	v_add_f32_e64 v120, v228, v120
	v_add_f32_e64 v121, v229, v121
	v_exp_f32_e32 v182, v96
	v_exp_f32_e32 v183, v97
	v_exp_f32_e32 v184, v98
	v_exp_f32_e32 v185, v99
	v_cvt_pk_bf16_f32 v96, v228, v229
	v_cvt_pk_bf16_f32 v97, v230, v231
	v_cvt_pk_bf16_f32 v98, v124, v125
	v_cvt_pk_bf16_f32 v99, v126, v127
	v_pk_add_f32 v[122:123], v[126:127], v[122:123]
	v_pk_add_f32 v[120:121], v[124:125], v[120:121]
	v_mfma_f32_32x32x16_bf16 v[128:143], v[216:219], v[168:171], v[128:143]
	v_exp_f32_e32 v124, v100
	v_exp_f32_e32 v125, v101
	v_exp_f32_e32 v126, v102
	v_exp_f32_e32 v127, v103
	v_mfma_f32_32x32x16_bf16 v[144:159], v[116:119], v[172:175], v[144:159]
	v_exp_f32_e32 v186, v104
	v_exp_f32_e32 v187, v105
	v_exp_f32_e32 v188, v106
	v_exp_f32_e32 v189, v107
	v_pk_add_f32 v[106:107], v[184:185], v[122:123]
	v_pk_add_f32 v[104:105], v[182:183], v[120:121]
	v_cvt_pk_bf16_f32 v100, v182, v183
	v_cvt_pk_bf16_f32 v101, v184, v185
	v_cvt_pk_bf16_f32 v102, v124, v125
	v_cvt_pk_bf16_f32 v103, v126, v127
	v_pk_add_f32 v[118:119], v[126:127], v[106:107]
	v_pk_add_f32 v[116:117], v[124:125], v[104:105]
	v_mfma_f32_32x32x16_bf16 v[128:143], v[176:179], v[172:175], v[128:143]
	v_exp_f32_e32 v120, v108
	v_exp_f32_e32 v121, v109
	v_exp_f32_e32 v122, v110
	v_exp_f32_e32 v123, v111
	v_pk_add_f32 v[110:111], v[188:189], v[118:119]
	v_pk_add_f32 v[108:109], v[186:187], v[116:117]
	v_cvt_pk_bf16_f32 v104, v186, v187
	v_cvt_pk_bf16_f32 v105, v188, v189
	v_cvt_pk_bf16_f32 v106, v120, v121
	v_cvt_pk_bf16_f32 v107, v122, v123
	s_mov_b64 s[44:45], -1
	s_and_b64 vcc, exec, s[42:43]
	v_pk_add_f32 v[178:179], v[122:123], v[110:111]
	v_pk_add_f32 v[176:177], v[120:121], v[108:109]
	s_cbranch_vccz .LBB0_918
	s_waitcnt vmcnt(2) lgkmcnt(0)
	s_mov_b64 s[44:45], 0

.LBB0_920:
	s_barrier
	s_cmp_gt_u32 s47, 63
	s_cselect_b64 s[44:45], -1, 0
	s_and_b64 vcc, exec, s[44:45]
	s_cbranch_vccnz .LBB0_922
	s_cmp_lt_u32 s47, 60
	s_cselect_b32 s69, s40, s21
	s_add_i32 s69, s69, s41
	s_mul_hi_i32 s71, s69, 0x600
	s_mulk_i32 s69, 0x600
	s_add_u32 s70, s14, s69
	s_addc_u32 s71, s15, s71
	s_add_i32 s68, s68, s57
	s_mov_b32 m0, s68
	s_nop 0
	global_load_lds_dwordx4 v198, s[70:71]
	s_add_i32 m0, s68, 0x400
	s_nop 0
	global_load_lds_dwordx4 v194, s[70:71]
.LBB0_922:
	s_andn2_b64 vcc, exec, s[2:3]
	s_cbranch_vccnz .LBB0_924
	s_cmp_lt_u32 s47, 61
	s_cselect_b32 s2, s40, s21
	s_add_i32 s2, s2, s41
	s_sub_i32 s2, s2, 64
	s_ashr_i32 s3, s2, 31
	s_lshl_b64 s[2:3], s[2:3], 1
	s_add_u32 s2, s39, s2
	s_addc_u32 s3, s67, s3
	s_add_i32 s49, s58, s49
	s_add_i32 m0, s49, 0xc000
	s_nop 0
	global_load_lds_dwordx4 v196, s[2:3]
	s_add_i32 m0, s49, 0xc400
	s_nop 0
	global_load_lds_dwordx4 v192, s[2:3]
.LBB0_924:
	s_add_i32 s2, s46, 0xffff4000
	s_add_i32 s3, s48, 1
	s_cmp_lg_u32 s48, 2
	s_cselect_b32 s48, s3, 0
	s_and_b32 s2, s2, 0xc000
	v_mov_b32_e32 v181, v206
	v_mov_b32_e32 v232, v205
	s_add_i32 s2, s2, 0
	s_lshl_b32 s3, s48, 14
	v_add_u32_e32 v124, s2, v181
	ds_read_b128 v[108:111], v124 offset:49152
	ds_read_b128 v[116:119], v124 offset:53248
	ds_read_b128 v[120:123], v124 offset:57344
	ds_read_b128 v[124:127], v124 offset:61440
	s_waitcnt lgkmcnt(0)
	v_mfma_f32_32x32x16_bf16 v[80:95], v[108:111], v[112:115], v[80:95]
	v_xad_u32 v182, v181, 32, s2
	ds_read_b128 v[108:111], v182 offset:49152
	s_add_i32 s3, s3, 0
	v_mfma_f32_32x32x16_bf16 v[64:79], v[116:119], v[112:115], v[64:79]
	ds_read_b128 v[116:119], v182 offset:53248
	v_mfma_f32_32x32x16_bf16 v[16:31], v[120:123], v[112:115], v[16:31]
	ds_read_b128 v[120:123], v182 offset:57344
	v_mfma_f32_32x32x16_bf16 v[0:15], v[124:127], v[112:115], v[0:15]
	ds_read_b128 v[112:115], v182 offset:61440
	s_waitcnt lgkmcnt(0)
	v_mfma_f32_32x32x16_bf16 v[80:95], v[108:111], v[96:99], v[80:95]
	v_xad_u32 v124, v181, 64, s2
	ds_read_b128 v[108:111], v124 offset:49152
	v_mfma_f32_32x32x16_bf16 v[64:79], v[116:119], v[96:99], v[64:79]
	ds_read_b128 v[116:119], v124 offset:53248
	v_mfma_f32_32x32x16_bf16 v[16:31], v[120:123], v[96:99], v[16:31]
	ds_read_b128 v[120:123], v124 offset:57344
	v_mfma_f32_32x32x16_bf16 v[0:15], v[112:115], v[96:99], v[0:15]
	ds_read_b128 v[96:99], v124 offset:61440
	s_waitcnt lgkmcnt(0)
	v_mfma_f32_32x32x16_bf16 v[80:95], v[108:111], v[100:103], v[80:95]
	v_xor_b32_e32 v108, 0x60, v181
	v_add_u32_e32 v124, s2, v108
	ds_read_b128 v[108:111], v124 offset:49152
	v_mfma_f32_32x32x16_bf16 v[64:79], v[116:119], v[100:103], v[64:79]
	ds_read_b128 v[112:115], v124 offset:53248
	v_mfma_f32_32x32x16_bf16 v[16:31], v[120:123], v[100:103], v[16:31]
	ds_read_b128 v[116:119], v124 offset:57344
	v_mfma_f32_32x32x16_bf16 v[0:15], v[96:99], v[100:103], v[0:15]
	ds_read_b128 v[120:123], v124 offset:61440
	s_waitcnt lgkmcnt(0)
	v_mfma_f32_32x32x16_bf16 v[80:95], v[108:111], v[104:107], v[80:95]
	v_add_u32_e32 v100, s3, v232
	ds_read_b128 v[96:99], v100
	v_mfma_f32_32x32x16_bf16 v[64:79], v[112:115], v[104:107], v[64:79]
	ds_read_b128 v[100:103], v100 offset:8192
	v_mfma_f32_32x32x16_bf16 v[16:31], v[116:119], v[104:107], v[16:31]
	v_xad_u32 v108, v232, 32, s3
	ds_read_b128 v[182:185], v108
	v_mfma_f32_32x32x16_bf16 v[0:15], v[120:123], v[104:107], v[0:15]
	ds_read_b128 v[186:189], v108 offset:8192
	s_waitcnt lgkmcnt(0)
	v_mfma_f32_32x32x16_bf16 v[112:127], v[96:99], v[160:163], 0
	v_xad_u32 v104, v232, 64, s3
	ds_read_b128 v[216:219], v104
	v_exp_f32_e32 v224, v144
	v_exp_f32_e32 v225, v145
	v_exp_f32_e32 v226, v146
	v_exp_f32_e32 v227, v147
	ds_read_b128 v[220:223], v104 offset:8192
	v_mfma_f32_32x32x16_bf16 v[96:111], v[100:103], v[160:163], 0
	v_exp_f32_e32 v228, v148
	v_exp_f32_e32 v229, v149
	v_exp_f32_e32 v230, v150
	v_exp_f32_e32 v231, v151
	v_mfma_f32_32x32x16_bf16 v[112:127], v[182:185], v[164:167], v[112:127]
	v_xor_b32_e32 v144, 0x60, v232
	v_add_u32_e32 v181, s3, v144
	ds_read_b128 v[148:151], v181
	v_exp_f32_e32 v232, v152
	v_exp_f32_e32 v233, v153
	v_exp_f32_e32 v234, v154
	v_exp_f32_e32 v235, v155
	v_pk_add_f32 v[154:155], v[226:227], 0 op_sel_hi:[1,0]
	v_pk_add_f32 v[152:153], v[224:225], 0 op_sel_hi:[1,0]
	v_cvt_pk_bf16_f32 v144, v224, v225
	v_cvt_pk_bf16_f32 v145, v226, v227
	v_cvt_pk_bf16_f32 v146, v228, v229
	v_cvt_pk_bf16_f32 v147, v230, v231
	v_pk_add_f32 v[154:155], v[230:231], v[154:155]
	v_pk_add_f32 v[152:153], v[228:229], v[152:153]
	v_mfma_f32_32x32x16_bf16 v[96:111], v[186:189], v[164:167], v[96:111]
	ds_read_b128 v[182:185], v181 offset:8192
	v_exp_f32_e32 v156, v156
	v_exp_f32_e32 v157, v157
	v_exp_f32_e32 v158, v158
	v_exp_f32_e32 v159, v159
	s_waitcnt lgkmcnt(0)
	v_mfma_f32_32x32x16_bf16 v[112:127], v[216:219], v[168:171], v[112:127]
	v_add_f32_e64 v154, v234, v154
	v_add_f32_e64 v155, v235, v155
	v_add_f32_e64 v152, v232, v152
	v_add_f32_e64 v153, v233, v153
	v_exp_f32_e32 v186, v128
	v_exp_f32_e32 v187, v129
	v_exp_f32_e32 v188, v130
	v_exp_f32_e32 v189, v131
	v_cvt_pk_bf16_f32 v128, v232, v233
	v_cvt_pk_bf16_f32 v129, v234, v235
	v_cvt_pk_bf16_f32 v130, v156, v157
	v_cvt_pk_bf16_f32 v131, v158, v159
	v_pk_add_f32 v[154:155], v[158:159], v[154:155]
	v_pk_add_f32 v[152:153], v[156:157], v[152:153]
	v_mfma_f32_32x32x16_bf16 v[96:111], v[220:223], v[168:171], v[96:111]
	v_exp_f32_e32 v156, v132
	v_exp_f32_e32 v157, v133
	v_exp_f32_e32 v158, v134
	v_exp_f32_e32 v159, v135
	v_mfma_f32_32x32x16_bf16 v[112:127], v[148:151], v[172:175], v[112:127]
	v_exp_f32_e32 v216, v136
	v_exp_f32_e32 v217, v137
	v_exp_f32_e32 v218, v138
	v_exp_f32_e32 v219, v139
	v_pk_add_f32 v[138:139], v[188:189], v[154:155]
	v_pk_add_f32 v[136:137], v[186:187], v[152:153]
	v_cvt_pk_bf16_f32 v132, v186, v187
	v_cvt_pk_bf16_f32 v133, v188, v189
	v_cvt_pk_bf16_f32 v134, v156, v157
	v_cvt_pk_bf16_f32 v135, v158, v159
	v_pk_add_f32 v[150:151], v[158:159], v[138:139]
	v_pk_add_f32 v[148:149], v[156:157], v[136:137]
	v_mfma_f32_32x32x16_bf16 v[96:111], v[182:185], v[172:175], v[96:111]
	v_exp_f32_e32 v152, v140
	v_exp_f32_e32 v153, v141
	v_exp_f32_e32 v154, v142
	v_exp_f32_e32 v155, v143
	v_pk_add_f32 v[142:143], v[218:219], v[150:151]
	v_pk_add_f32 v[140:141], v[216:217], v[148:149]
	v_cvt_pk_bf16_f32 v136, v216, v217
	v_cvt_pk_bf16_f32 v137, v218, v219
	v_cvt_pk_bf16_f32 v138, v152, v153
	v_cvt_pk_bf16_f32 v139, v154, v155
	s_mov_b64 s[2:3], -1
	s_and_b64 vcc, exec, s[44:45]
	v_pk_add_f32 v[142:143], v[154:155], v[142:143]
	v_pk_add_f32 v[140:141], v[152:153], v[140:141]
	s_cbranch_vccz .LBB0_930
	s_and_b64 vcc, exec, s[42:43]
	s_cbranch_vccz .LBB0_927
	s_waitcnt vmcnt(0) lgkmcnt(0)
	s_mov_b64 s[2:3], 0

.LBB0_936:
	s_cmpk_lt_u32 s21, 0x41
	s_cselect_b64 s[44:45], -1, 0
	s_cmp_gt_u32 s21, 64
	s_cselect_b64 s[42:43], -1, 0
	s_and_b64 vcc, exec, s[42:43]
	s_cbranch_vccnz .LBB0_938
	s_cmp_lt_u32 s21, 61
	s_cselect_b32 s2, s40, s14
	s_add_i32 s2, s2, s15
	s_sub_i32 s2, s2, 64
	s_mul_hi_i32 s3, s2, 0x600
	s_mulk_i32 s2, 0x600
	s_add_u32 s2, s12, s2
	s_addc_u32 s3, s13, s3
	s_lshl_b32 s46, s41, 14
	s_add_i32 s46, s58, s46
	s_mov_b32 m0, s46
	s_nop 0
	global_load_lds_dwordx4 v198, s[2:3]
	s_add_i32 m0, s46, 0x400
	s_nop 0
	global_load_lds_dwordx4 v194, s[2:3]
.LBB0_938:
	s_cmpk_gt_u32 s21, 0x41
	s_cselect_b64 s[2:3], -1, 0
	s_and_b64 vcc, exec, s[2:3]
	s_cbranch_vccnz .LBB0_940
	s_cmp_lt_u32 s21, 62
	s_cselect_b32 s46, s40, s14
	s_add_i32 s46, s46, s15
	s_addk_i32 s46, 0xff80
	s_ashr_i32 s47, s46, 31
	s_lshl_b64 s[46:47], s[46:47], 1
	s_add_u32 s46, s39, s46
	s_addc_u32 s47, s67, s47
	s_add_i32 s48, s20, 0xffffc000
	s_and_b32 s48, s48, 0x8000
	s_add_i32 s48, s58, s48
	s_add_i32 m0, s48, 0xc000
	s_nop 0
	global_load_lds_dwordx4 v196, s[46:47]
	s_add_i32 m0, s48, 0xc400
	s_nop 0
	global_load_lds_dwordx4 v192, s[46:47]
.LBB0_940:
	s_add_i32 s46, s41, 1
	s_cmp_lg_u32 s41, 2
	s_cselect_b32 s41, s46, 0
	s_lshl_b32 s46, s41, 14
	s_add_i32 s49, s46, 0
	v_mov_b32_e32 v148, v205
	v_mov_b32_e32 v176, v206
	s_add_i32 s46, s20, 0xffff4000
	v_add_u32_e32 v100, s49, v148
	ds_read_b128 v[96:99], v100
	ds_read_b128 v[100:103], v100 offset:8192
	s_waitcnt lgkmcnt(0)
	v_mfma_f32_32x32x16_bf16 v[112:127], v[96:99], v[160:163], 0
	v_xad_u32 v104, v148, 32, s49
	ds_read_b128 v[128:131], v104
	ds_read_b128 v[132:135], v104 offset:8192
	v_xad_u32 v96, v148, 64, s49
	ds_read_b128 v[136:139], v96
	s_and_b32 s46, s46, 0x8000
	s_add_i32 s48, s46, 0
	v_exp_f32_e32 v140, v48
	v_exp_f32_e32 v141, v49
	v_exp_f32_e32 v142, v50
	v_exp_f32_e32 v143, v51
	ds_read_b128 v[48:51], v96 offset:8192
	v_mfma_f32_32x32x16_bf16 v[96:111], v[100:103], v[160:163], 0
	v_exp_f32_e32 v144, v52
	v_exp_f32_e32 v145, v53
	v_exp_f32_e32 v146, v54
	v_exp_f32_e32 v147, v55
	s_waitcnt lgkmcnt(0)
	v_mfma_f32_32x32x16_bf16 v[112:127], v[128:131], v[164:167], v[112:127]
	v_xor_b32_e32 v52, 0x60, v148
	v_add_u32_e32 v152, s49, v52
	ds_read_b128 v[52:55], v152
	v_exp_f32_e32 v148, v56
	v_exp_f32_e32 v149, v57
	v_exp_f32_e32 v150, v58
	v_exp_f32_e32 v151, v59
	v_mfma_f32_32x32x16_bf16 v[96:111], v[132:135], v[164:167], v[96:111]
	ds_read_b128 v[56:59], v152 offset:8192
	v_exp_f32_e32 v128, v60
	v_exp_f32_e32 v129, v61
	v_exp_f32_e32 v130, v62
	v_exp_f32_e32 v131, v63
	v_mfma_f32_32x32x16_bf16 v[112:127], v[136:139], v[168:171], v[112:127]
	v_add_u32_e32 v156, s48, v176
	ds_read_b128 v[60:63], v156 offset:49152
	v_exp_f32_e32 v132, v32
	v_exp_f32_e32 v133, v33
	v_exp_f32_e32 v134, v34
	v_exp_f32_e32 v135, v35
	v_mfma_f32_32x32x16_bf16 v[96:111], v[48:51], v[168:171], v[96:111]
	ds_read_b128 v[32:35], v156 offset:53248
	v_exp_f32_e32 v136, v36
	v_exp_f32_e32 v137, v37
	v_exp_f32_e32 v138, v38
	v_exp_f32_e32 v139, v39
	s_waitcnt lgkmcnt(0)
	v_mfma_f32_32x32x16_bf16 v[112:127], v[52:55], v[172:175], v[112:127]
	ds_read_b128 v[36:39], v156 offset:57344
	v_exp_f32_e32 v152, v40
	v_exp_f32_e32 v153, v41
	v_exp_f32_e32 v154, v42
	v_exp_f32_e32 v155, v43
	v_mfma_f32_32x32x16_bf16 v[96:111], v[56:59], v[172:175], v[96:111]
	ds_read_b128 v[40:43], v156 offset:61440
	v_exp_f32_e32 v156, v44
	v_exp_f32_e32 v157, v45
	v_exp_f32_e32 v158, v46
	v_exp_f32_e32 v159, v47
	v_cvt_pk_bf16_f32 v44, v140, v141
	v_cvt_pk_bf16_f32 v45, v142, v143
	v_cvt_pk_bf16_f32 v46, v144, v145
	v_cvt_pk_bf16_f32 v47, v146, v147
	s_nop 1
	v_mfma_f32_32x32x16_bf16 v[80:95], v[60:63], v[44:47], v[80:95]
	v_xad_u32 v178, v176, 32, s48
	ds_read_b128 v[48:51], v178 offset:49152
	v_cvt_pk_bf16_f32 v52, v148, v149
	v_cvt_pk_bf16_f32 v53, v150, v151
	v_cvt_pk_bf16_f32 v54, v128, v129
	v_cvt_pk_bf16_f32 v55, v130, v131
	v_mfma_f32_32x32x16_bf16 v[64:79], v[32:35], v[44:47], v[64:79]
	ds_read_b128 v[56:59], v178 offset:53248
	v_add_f32_e64 v62, v142, 0
	v_add_f32_e64 v63, v143, 0
	v_add_f32_e64 v60, v140, 0
	v_add_f32_e64 v61, v141, 0
	v_pk_add_f32 v[62:63], v[146:147], v[62:63]
	v_pk_add_f32 v[60:61], v[144:145], v[60:61]
	s_waitcnt lgkmcnt(0)
	v_mfma_f32_32x32x16_bf16 v[16:31], v[36:39], v[44:47], v[16:31]
	ds_read_b128 v[32:35], v178 offset:57344
	v_add_f32_e64 v62, v150, v62
	v_add_f32_e64 v63, v151, v63
	v_add_f32_e64 v60, v148, v60
	v_add_f32_e64 v61, v149, v61
	v_pk_add_f32 v[62:63], v[130:131], v[62:63]
	v_pk_add_f32 v[60:61], v[128:129], v[60:61]
	v_mfma_f32_32x32x16_bf16 v[0:15], v[40:43], v[44:47], v[0:15]
	ds_read_b128 v[36:39], v178 offset:61440
	v_mfma_f32_32x32x16_bf16 v[80:95], v[48:51], v[52:55], v[80:95]
	v_xad_u32 v140, v176, 64, s48
	ds_read_b128 v[40:43], v140 offset:49152
	v_cvt_pk_bf16_f32 v44, v132, v133
	v_cvt_pk_bf16_f32 v45, v134, v135
	v_cvt_pk_bf16_f32 v46, v136, v137
	v_cvt_pk_bf16_f32 v47, v138, v139
	v_mfma_f32_32x32x16_bf16 v[64:79], v[56:59], v[52:55], v[64:79]
	ds_read_b128 v[48:51], v140 offset:53248
	v_add_f32_e64 v62, v134, v62
	v_add_f32_e64 v63, v135, v63
	v_add_f32_e64 v60, v132, v60
	v_add_f32_e64 v61, v133, v61
	v_pk_add_f32 v[62:63], v[138:139], v[62:63]
	v_pk_add_f32 v[60:61], v[136:137], v[60:61]
	s_waitcnt lgkmcnt(0)
	v_mfma_f32_32x32x16_bf16 v[16:31], v[32:35], v[52:55], v[16:31]
	ds_read_b128 v[56:59], v140 offset:57344
	v_add_f32_e64 v62, v154, v62
	v_add_f32_e64 v63, v155, v63
	v_add_f32_e64 v60, v152, v60
	v_add_f32_e64 v61, v153, v61
	v_pk_add_f32 v[130:131], v[158:159], v[62:63]
	v_pk_add_f32 v[128:129], v[156:157], v[60:61]
	v_mfma_f32_32x32x16_bf16 v[0:15], v[36:39], v[52:55], v[0:15]
	ds_read_b128 v[32:35], v140 offset:61440
	v_mfma_f32_32x32x16_bf16 v[80:95], v[40:43], v[44:47], v[80:95]
	v_xor_b32_e32 v36, 0x60, v176
	v_add_u32_e32 v60, s48, v36
	ds_read_b128 v[36:39], v60 offset:49152
	v_cvt_pk_bf16_f32 v52, v152, v153
	v_cvt_pk_bf16_f32 v53, v154, v155
	v_cvt_pk_bf16_f32 v54, v156, v157
	v_cvt_pk_bf16_f32 v55, v158, v159
	v_mfma_f32_32x32x16_bf16 v[64:79], v[48:51], v[44:47], v[64:79]
	ds_read_b128 v[40:43], v60 offset:53248
	s_waitcnt lgkmcnt(0)
	v_mfma_f32_32x32x16_bf16 v[16:31], v[56:59], v[44:47], v[16:31]
	ds_read_b128 v[48:51], v60 offset:57344
	v_mfma_f32_32x32x16_bf16 v[0:15], v[32:35], v[44:47], v[0:15]
	ds_read_b128 v[56:59], v60 offset:61440
	v_mfma_f32_32x32x16_bf16 v[80:95], v[36:39], v[52:55], v[80:95]
	v_mfma_f32_32x32x16_bf16 v[64:79], v[40:43], v[52:55], v[64:79]
	s_waitcnt lgkmcnt(0)
	v_mfma_f32_32x32x16_bf16 v[16:31], v[48:51], v[52:55], v[16:31]
	v_mfma_f32_32x32x16_bf16 v[0:15], v[56:59], v[52:55], v[0:15]
	s_mov_b64 s[46:47], -1
	s_and_b64 vcc, exec, s[42:43]
	s_cbranch_vccz .LBB0_946
	s_and_b64 vcc, exec, s[2:3]
	s_cbranch_vccz .LBB0_943
	s_waitcnt vmcnt(0) lgkmcnt(0)
	s_mov_b64 s[46:47], 0

.LBB0_948:
	s_barrier
	s_cmp_gt_u32 s21, 63
	s_cselect_b64 s[46:47], -1, 0
	s_and_b64 vcc, exec, s[46:47]
	s_cbranch_vccnz .LBB0_950
	s_cmp_lt_u32 s21, 60
	s_cselect_b32 s68, s40, s14
	s_add_i32 s68, s68, s15
	s_mul_hi_i32 s69, s68, 0x600
	s_mulk_i32 s68, 0x600
	s_add_u32 s68, s12, s68
	s_addc_u32 s69, s13, s69
	s_add_i32 s49, s49, s57
	s_mov_b32 m0, s49
	s_nop 0
	global_load_lds_dwordx4 v198, s[68:69]
	s_add_i32 m0, s49, 0x400
	s_nop 0
	global_load_lds_dwordx4 v194, s[68:69]
.LBB0_950:
	s_andn2_b64 vcc, exec, s[44:45]
	s_cbranch_vccnz .LBB0_952
	s_cmp_lt_u32 s21, 61
	s_cselect_b32 s44, s40, s14
	s_add_i32 s44, s44, s15
	s_sub_i32 s44, s44, 64
	s_ashr_i32 s45, s44, 31
	s_lshl_b64 s[44:45], s[44:45], 1
	s_add_u32 s44, s39, s44
	s_addc_u32 s45, s67, s45
	s_and_b32 s49, s20, 0xc000
	s_add_i32 s49, s58, s49
	s_add_i32 m0, s49, 0xc000
	s_nop 0
	global_load_lds_dwordx4 v196, s[44:45]
	s_add_i32 m0, s49, 0xc400
	s_nop 0
	global_load_lds_dwordx4 v192, s[44:45]
.LBB0_952:
	s_add_i32 s48, s48, 0xc000
	s_add_i32 s44, s41, 1
	s_cmp_lg_u32 s41, 2
	s_cselect_b32 s41, s44, 0
	s_lshl_b32 s44, s41, 14
	s_add_i32 s44, s44, 0
	v_mov_b32_e32 v152, v205
	v_mov_b32_e32 v176, v206
	v_exp_f32_e32 v144, v112
	v_add_u32_e32 v36, s44, v152
	ds_read_b128 v[32:35], v36
	ds_read_b128 v[36:39], v36 offset:8192
	s_waitcnt lgkmcnt(0)
	v_mfma_f32_32x32x16_bf16 v[48:63], v[32:35], v[160:163], 0
	v_xad_u32 v40, v152, 32, s44
	ds_read_b128 v[132:135], v40
	ds_read_b128 v[136:139], v40 offset:8192
	v_xad_u32 v32, v152, 64, s44
	ds_read_b128 v[140:143], v32
	v_exp_f32_e32 v145, v113
	v_exp_f32_e32 v146, v114
	v_exp_f32_e32 v147, v115
	ds_read_b128 v[112:115], v32 offset:8192
	v_mfma_f32_32x32x16_bf16 v[32:47], v[36:39], v[160:163], 0
	v_exp_f32_e32 v148, v116
	v_exp_f32_e32 v149, v117
	v_exp_f32_e32 v150, v118
	v_exp_f32_e32 v151, v119
	s_waitcnt lgkmcnt(0)
	v_mfma_f32_32x32x16_bf16 v[48:63], v[132:135], v[164:167], v[48:63]
	v_xor_b32_e32 v116, 0x60, v152
	v_add_u32_e32 v156, s44, v116
	ds_read_b128 v[116:119], v156
	v_exp_f32_e32 v152, v120
	v_exp_f32_e32 v153, v121
	v_exp_f32_e32 v154, v122
	v_exp_f32_e32 v155, v123
	v_mfma_f32_32x32x16_bf16 v[32:47], v[136:139], v[164:167], v[32:47]
	ds_read_b128 v[120:123], v156 offset:8192
	v_exp_f32_e32 v156, v124
	v_exp_f32_e32 v157, v125
	v_exp_f32_e32 v158, v126
	v_exp_f32_e32 v159, v127
	v_mfma_f32_32x32x16_bf16 v[48:63], v[140:143], v[168:171], v[48:63]
	v_add_u32_e32 v132, s48, v176
	ds_read_b128 v[124:127], v132 offset:16384
	v_exp_f32_e32 v136, v96
	v_exp_f32_e32 v137, v97
	v_exp_f32_e32 v138, v98
	v_exp_f32_e32 v139, v99
	v_mfma_f32_32x32x16_bf16 v[32:47], v[112:115], v[168:171], v[32:47]
	ds_read_b128 v[96:99], v132 offset:20480
	v_exp_f32_e32 v140, v100
	v_exp_f32_e32 v141, v101
	v_exp_f32_e32 v142, v102
	v_exp_f32_e32 v143, v103
	s_waitcnt lgkmcnt(0)
	v_mfma_f32_32x32x16_bf16 v[48:63], v[116:119], v[172:175], v[48:63]
	ds_read_b128 v[100:103], v132 offset:24576
	v_exp_f32_e32 v178, v104
	v_exp_f32_e32 v179, v105
	v_exp_f32_e32 v180, v106
	v_exp_f32_e32 v181, v107
	v_mfma_f32_32x32x16_bf16 v[32:47], v[120:123], v[172:175], v[32:47]
	ds_read_b128 v[104:107], v132 offset:28672
	v_exp_f32_e32 v182, v108
	v_exp_f32_e32 v183, v109
	v_exp_f32_e32 v184, v110
	v_exp_f32_e32 v185, v111
	v_cvt_pk_bf16_f32 v108, v144, v145
	v_cvt_pk_bf16_f32 v109, v146, v147
	v_cvt_pk_bf16_f32 v110, v148, v149
	v_cvt_pk_bf16_f32 v111, v150, v151
	s_nop 1
	v_mfma_f32_32x32x16_bf16 v[80:95], v[124:127], v[108:111], v[80:95]
	v_xad_u32 v186, v176, 32, s48
	ds_read_b128 v[112:115], v186 offset:16384
	v_cvt_pk_bf16_f32 v116, v152, v153
	v_cvt_pk_bf16_f32 v117, v154, v155
	v_cvt_pk_bf16_f32 v118, v156, v157
	v_cvt_pk_bf16_f32 v119, v158, v159
	v_mfma_f32_32x32x16_bf16 v[64:79], v[96:99], v[108:111], v[64:79]
	ds_read_b128 v[120:123], v186 offset:20480
	v_add_f32_e64 v126, v146, 0
	v_add_f32_e64 v127, v147, 0
	v_add_f32_e64 v124, v144, 0
	v_add_f32_e64 v125, v145, 0
	v_pk_add_f32 v[126:127], v[150:151], v[126:127]
	v_pk_add_f32 v[124:125], v[148:149], v[124:125]
	s_waitcnt lgkmcnt(0)
	v_mfma_f32_32x32x16_bf16 v[16:31], v[100:103], v[108:111], v[16:31]
	ds_read_b128 v[132:135], v186 offset:24576
	v_add_f32_e64 v98, v154, v126
	v_add_f32_e64 v99, v155, v127
	v_add_f32_e64 v96, v152, v124
	v_add_f32_e64 v97, v153, v125
	v_pk_add_f32 v[98:99], v[158:159], v[98:99]
	v_pk_add_f32 v[96:97], v[156:157], v[96:97]
	v_mfma_f32_32x32x16_bf16 v[0:15], v[104:107], v[108:111], v[0:15]
	ds_read_b128 v[100:103], v186 offset:28672
	v_mfma_f32_32x32x16_bf16 v[80:95], v[112:115], v[116:119], v[80:95]
	v_xad_u32 v124, v176, 64, s48
	ds_read_b128 v[104:107], v124 offset:16384
	v_cvt_pk_bf16_f32 v108, v136, v137
	v_cvt_pk_bf16_f32 v109, v138, v139
	v_cvt_pk_bf16_f32 v110, v140, v141
	v_cvt_pk_bf16_f32 v111, v142, v143
	v_mfma_f32_32x32x16_bf16 v[64:79], v[120:123], v[116:119], v[64:79]
	ds_read_b128 v[112:115], v124 offset:20480
	v_add_f32_e64 v98, v138, v98
	v_add_f32_e64 v99, v139, v99
	v_add_f32_e64 v96, v136, v96
	v_add_f32_e64 v97, v137, v97
	v_pk_add_f32 v[98:99], v[142:143], v[98:99]
	v_pk_add_f32 v[96:97], v[140:141], v[96:97]
	s_waitcnt lgkmcnt(0)
	v_mfma_f32_32x32x16_bf16 v[16:31], v[132:135], v[116:119], v[16:31]
	ds_read_b128 v[120:123], v124 offset:24576
	v_add_f32_e64 v98, v180, v98
	v_add_f32_e64 v99, v181, v99
	v_add_f32_e64 v96, v178, v96
	v_add_f32_e64 v97, v179, v97
	v_pk_add_f32 v[98:99], v[184:185], v[98:99]
	v_pk_add_f32 v[96:97], v[182:183], v[96:97]
	v_mfma_f32_32x32x16_bf16 v[0:15], v[100:103], v[116:119], v[0:15]
	ds_read_b128 v[124:127], v124 offset:28672
	v_mfma_f32_32x32x16_bf16 v[80:95], v[104:107], v[108:111], v[80:95]
	v_xor_b32_e32 v100, 0x60, v176
	v_add_u32_e32 v132, s48, v100
	ds_read_b128 v[100:103], v132 offset:16384
	v_cvt_pk_bf16_f32 v116, v178, v179
	v_cvt_pk_bf16_f32 v117, v180, v181
	v_cvt_pk_bf16_f32 v118, v182, v183
	v_cvt_pk_bf16_f32 v119, v184, v185
	v_mfma_f32_32x32x16_bf16 v[64:79], v[112:115], v[108:111], v[64:79]
	ds_read_b128 v[104:107], v132 offset:20480
	s_waitcnt lgkmcnt(0)
	v_mfma_f32_32x32x16_bf16 v[16:31], v[120:123], v[108:111], v[16:31]
	ds_read_b128 v[112:115], v132 offset:24576
	v_mfma_f32_32x32x16_bf16 v[0:15], v[124:127], v[108:111], v[0:15]
	ds_read_b128 v[120:123], v132 offset:28672
	v_mfma_f32_32x32x16_bf16 v[80:95], v[100:103], v[116:119], v[80:95]
	v_mfma_f32_32x32x16_bf16 v[64:79], v[104:107], v[116:119], v[64:79]
	s_waitcnt lgkmcnt(0)
	v_mfma_f32_32x32x16_bf16 v[16:31], v[112:115], v[116:119], v[16:31]
	v_mfma_f32_32x32x16_bf16 v[0:15], v[120:123], v[116:119], v[0:15]
	s_mov_b64 s[44:45], -1
	s_and_b64 vcc, exec, s[46:47]
	s_cbranch_vccz .LBB0_958
	s_and_b64 vcc, exec, s[42:43]
	s_cbranch_vccz .LBB0_955
	s_waitcnt vmcnt(0) lgkmcnt(0)
	s_mov_b64 s[44:45], 0
